# attention 16x16x32 loop: lgkmcnt wait every other MFMA pair (12 instead of 24 s_waitcnt per tile)
# speedup vs baseline: 1.0209x; 1.0017x over previous
; #define SB() __builtin_amdgcn_sched_barrier(0)
; __device__ __forceinline__ void attn_unit(unsigned char* ws, const float* sub_g, LAS unsigned char* lds, int h, int qb, float negM, float lam) {
;     ...
;         bf16x8 F0 = FLOAD(0), F1 = FLOAD(1), F2;
;         SB();
;         F2 = FLOAD(2); s0 = __builtin_amdgcn_mfma_f32_32x32x16_bf16(F0, qf[0], negm, 0, 0, 0); ADD4(pa, 0); pw[0][0] = cvtpk(pa[0], pa[1]); SB();
;         F0 = FLOAD(3); s1 = __builtin_amdgcn_mfma_f32_32x32x16_bf16(F1, qf[0], negm, 0, 0, 0); ADD4(pa, 4); pw[0][1] = cvtpk(pa[2], pa[3]); SB();
;         F1 = FLOAD(4); s0 = __builtin_amdgcn_mfma_f32_32x32x16_bf16(F2, qf[1], s0, 0, 0, 0); ADD4(pa, 8); pw[0][2] = cvtpk(pa[4], pa[5]); SB();
;         F2 = FLOAD(5); s1 = __builtin_amdgcn_mfma_f32_32x32x16_bf16(F0, qf[1], s1, 0, 0, 0); ADD4(pa, 12); pw[0][3] = cvtpk(pa[6], pa[7]); SB();
;         F0 = FLOAD(6); s0 = __builtin_amdgcn_mfma_f32_32x32x16_bf16(F1, qf[2], s0, 0, 0, 0); ADD4(pb, 0); pw[1][0] = cvtpk(pa[8], pa[9]); SB();
;         F1 = FLOAD(7); s1 = __builtin_amdgcn_mfma_f32_32x32x16_bf16(F2, qf[2], s1, 0, 0, 0); ADD4(pb, 4); pw[1][1] = cvtpk(pa[10], pa[11]); SB();
;         F2 = FLOAD(8); s0 = __builtin_amdgcn_mfma_f32_32x32x16_bf16(F0, qf[3], s0, 0, 0, 0); ADD4(pb, 8); pw[1][2] = cvtpk(pa[12], pa[13]); SB();
;         F0 = FLOAD(9); s1 = __builtin_amdgcn_mfma_f32_32x32x16_bf16(F1, qf[3], s1, 0, 0, 0); ADD4(pb, 12); pw[1][3] = cvtpk(pa[14], pa[15]); SB();
;         F1 = FLOAD(10); o[0] = __builtin_amdgcn_mfma_f32_32x32x16_bf16(F2, __builtin_bit_cast(bf16x8, pw[0]), o[0], 0, 0, 0); pw[2][0] = cvtpk(pb[0], pb[1]); EXP2(s0, pa, 0); SB();
;         F2 = FLOAD(11); o[1] = __builtin_amdgcn_mfma_f32_32x32x16_bf16(F0, __builtin_bit_cast(bf16x8, pw[0]), o[1], 0, 0, 0); pw[2][1] = cvtpk(pb[2], pb[3]); EXP2(s0, pa, 2); SB();
;         F0 = FLOAD(12); o[2] = __builtin_amdgcn_mfma_f32_32x32x16_bf16(F1, __builtin_bit_cast(bf16x8, pw[0]), o[2], 0, 0, 0); pw[2][2] = cvtpk(pb[4], pb[5]); EXP2(s0, pa, 4); SB();
;         F1 = FLOAD(13); o[3] = __builtin_amdgcn_mfma_f32_32x32x16_bf16(F2, __builtin_bit_cast(bf16x8, pw[0]), o[3], 0, 0, 0); pw[2][3] = cvtpk(pb[6], pb[7]); EXP2(s0, pa, 6); SB();
;         F2 = FLOAD(14); o[0] = __builtin_amdgcn_mfma_f32_32x32x16_bf16(F0, __builtin_bit_cast(bf16x8, pw[1]), o[0], 0, 0, 0); pw[3][0] = cvtpk(pb[8], pb[9]); EXP2(s0, pa, 8); SB();
.Lattn_c1:
	s_waitcnt lgkmcnt(1)
	v_mfma_f32_16x16x32_bf16 v[80:83], v[4:7], v[112:115], v[0:3]
	ds_read_b128 v[224:227], v200 offset:34816
	v_add_f32_e32 v222, v222, v183
	v_add_f32_e32 v223, v223, v187
	v_cvt_pk_bf16_f32 v232, v183, v184
	v_mfma_f32_16x16x32_bf16 v[84:87], v[4:7], v[120:123], v[0:3]
	v_add_f32_e32 v222, v222, v184
	v_add_f32_e32 v223, v223, v188
	v_mfma_f32_16x16x32_bf16 v[80:83], v[8:11], v[116:119], v[80:83]
	ds_read_b128 v[4:7], v198 offset:40960
	v_add_f32_e32 v222, v222, v185
	v_add_f32_e32 v223, v223, v189
	v_cvt_pk_bf16_f32 v233, v185, v186
	v_mfma_f32_16x16x32_bf16 v[84:87], v[8:11], v[124:127], v[84:87]
	v_add_f32_e32 v222, v222, v186
	v_add_f32_e32 v223, v223, v190
	s_waitcnt lgkmcnt(1)
	v_mfma_f32_16x16x32_bf16 v[88:91], v[12:15], v[112:115], v[0:3]
	ds_read_b128 v[8:11], v200 offset:40960
	v_add_f32_e32 v222, v222, v191
	v_add_f32_e32 v223, v223, v195
	v_cvt_pk_bf16_f32 v234, v191, v192
	v_mfma_f32_16x16x32_bf16 v[92:95], v[12:15], v[120:123], v[0:3]
	v_add_f32_e32 v222, v222, v192
	v_add_f32_e32 v223, v223, v196
	v_mfma_f32_16x16x32_bf16 v[88:91], v[224:227], v[116:119], v[88:91]
	ds_read_b128 v[12:15], v198 offset:43008
	v_add_f32_e32 v222, v222, v193
	v_add_f32_e32 v223, v223, v197
	v_cvt_pk_bf16_f32 v235, v193, v194
	v_mfma_f32_16x16x32_bf16 v[92:95], v[224:227], v[124:127], v[92:95]
	v_add_f32_e32 v222, v222, v194
	v_add_f32_e32 v223, v223, v199
	s_waitcnt lgkmcnt(1)
	v_mfma_f32_16x16x32_bf16 v[96:99], v[4:7], v[112:115], v[0:3]
	ds_read_b128 v[224:227], v200 offset:43008
	v_add_f32_e32 v222, v222, v203
	v_add_f32_e32 v223, v223, v207
	v_cvt_pk_bf16_f32 v236, v187, v188
	v_mfma_f32_16x16x32_bf16 v[100:103], v[4:7], v[120:123], v[0:3]
	v_add_f32_e32 v222, v222, v204
	v_add_f32_e32 v223, v223, v208
	v_mfma_f32_16x16x32_bf16 v[96:99], v[8:11], v[116:119], v[96:99]
	ds_read_b128 v[4:7], v201 offset:16384
	v_add_f32_e32 v222, v222, v205
	v_add_f32_e32 v223, v223, v209
	v_cvt_pk_bf16_f32 v237, v189, v190
	v_mfma_f32_16x16x32_bf16 v[100:103], v[8:11], v[124:127], v[100:103]
	v_add_f32_e32 v222, v222, v206
	v_add_f32_e32 v223, v223, v210
	s_waitcnt lgkmcnt(1)
	v_mfma_f32_16x16x32_bf16 v[104:107], v[12:15], v[112:115], v[0:3]
	ds_read_b128 v[8:11], v201 offset:18432
	v_add_f32_e32 v222, v222, v211
	v_add_f32_e32 v223, v223, v216
	v_cvt_pk_bf16_f32 v238, v195, v196
	v_mfma_f32_16x16x32_bf16 v[108:111], v[12:15], v[120:123], v[0:3]
	v_add_f32_e32 v222, v222, v213
	v_add_f32_e32 v223, v223, v217
	v_mfma_f32_16x16x32_bf16 v[104:107], v[224:227], v[116:119], v[104:107]
	ds_read_b128 v[12:15], v201 offset:20480
	v_add_f32_e32 v222, v222, v214
	v_add_f32_e32 v223, v223, v218
	v_cvt_pk_bf16_f32 v239, v197, v199
	v_mfma_f32_16x16x32_bf16 v[108:111], v[224:227], v[124:127], v[108:111]
	v_add_f32_e32 v222, v222, v215
	v_add_f32_e32 v223, v223, v219
	s_waitcnt vmcnt(0)
	s_barrier
	s_waitcnt lgkmcnt(1)
	v_mfma_f32_16x16x32_bf16 v[64:67], v[4:7], v[232:235], v[64:67]
	s_add_i32 m0, s8, 0x18000
	ds_read_b128 v[224:227], v201 offset:22528
	global_load_lds_dwordx4 v140, s[98:99]
	v_exp_f32_e32 v183, v80
	v_cvt_pk_bf16_f32 v228, v203, v204
	v_mfma_f32_16x16x32_bf16 v[68:71], v[4:7], v[236:239], v[68:71]
	v_exp_f32_e32 v184, v81
	v_mfma_f32_16x16x32_bf16 v[72:75], v[8:11], v[232:235], v[72:75]
	s_add_i32 m0, m0, 0x4000
	ds_read_b128 v[4:7], v201 offset:24576
	global_load_lds_dwordx4 v144, s[100:101]
	v_exp_f32_e32 v185, v82
	v_cvt_pk_bf16_f32 v229, v205, v206
	v_mfma_f32_16x16x32_bf16 v[76:79], v[8:11], v[236:239], v[76:79]
	v_exp_f32_e32 v186, v83
	s_waitcnt lgkmcnt(1)
	v_mfma_f32_16x16x32_bf16 v[48:51], v[12:15], v[232:235], v[48:51]
	s_add_i32 m0, m0, 0xffffc400
	ds_read_b128 v[8:11], v201 offset:26624
	global_load_lds_dwordx4 v142, s[98:99]
	v_exp_f32_e32 v187, v84
	v_cvt_pk_bf16_f32 v230, v211, v213
	v_mfma_f32_16x16x32_bf16 v[52:55], v[12:15], v[236:239], v[52:55]
	v_exp_f32_e32 v188, v85
	v_mfma_f32_16x16x32_bf16 v[56:59], v[224:227], v[232:235], v[56:59]
	s_add_i32 m0, m0, 0x4000
	ds_read_b128 v[12:15], v201 offset:28672
	global_load_lds_dwordx4 v146, s[100:101]
	s_add_u32 s98, s98, 0x20000
	s_addc_u32 s99, s99, 0
	s_add_u32 s100, s100, 0x80
	s_addc_u32 s101, s101, 0
	v_exp_f32_e32 v189, v86
	v_cvt_pk_bf16_f32 v231, v214, v215
	v_mfma_f32_16x16x32_bf16 v[60:63], v[224:227], v[236:239], v[60:63]
	v_exp_f32_e32 v190, v87
	s_waitcnt lgkmcnt(1)
	v_mfma_f32_16x16x32_bf16 v[32:35], v[4:7], v[232:235], v[32:35]
	ds_read_b128 v[224:227], v201 offset:30720
	v_exp_f32_e32 v191, v88
	v_cvt_pk_bf16_f32 v240, v207, v208
	v_mfma_f32_16x16x32_bf16 v[36:39], v[4:7], v[236:239], v[36:39]
	v_exp_f32_e32 v192, v89
	v_mfma_f32_16x16x32_bf16 v[40:43], v[8:11], v[232:235], v[40:43]
	ds_read_b128 v[4:7], v202 offset:16384
	v_exp_f32_e32 v193, v90
	v_cvt_pk_bf16_f32 v241, v209, v210
	v_mfma_f32_16x16x32_bf16 v[44:47], v[8:11], v[236:239], v[44:47]
	v_exp_f32_e32 v194, v91
	s_waitcnt lgkmcnt(1)
	v_mfma_f32_16x16x32_bf16 v[16:19], v[12:15], v[232:235], v[16:19]
	ds_read_b128 v[8:11], v202 offset:18432
	v_exp_f32_e32 v195, v92
	v_cvt_pk_bf16_f32 v242, v216, v217
	v_mfma_f32_16x16x32_bf16 v[20:23], v[12:15], v[236:239], v[20:23]
	v_exp_f32_e32 v196, v93
	v_mfma_f32_16x16x32_bf16 v[24:27], v[224:227], v[232:235], v[24:27]
	ds_read_b128 v[12:15], v202 offset:20480
	v_exp_f32_e32 v197, v94
	v_cvt_pk_bf16_f32 v243, v218, v219
	v_mfma_f32_16x16x32_bf16 v[28:31], v[224:227], v[236:239], v[28:31]
	v_exp_f32_e32 v199, v95
	s_waitcnt lgkmcnt(1)
; #define SB() __builtin_amdgcn_sched_barrier(0)
; __device__ __forceinline__ void attn_unit(unsigned char* ws, const float* sub_g, LAS unsigned char* lds, int h, int qb, float negM, float lam) {
;     ...
;         bf16x8 F0 = FLOAD(0), F1 = FLOAD(1), F2;
;         SB();
;         F2 = FLOAD(2); s0 = __builtin_amdgcn_mfma_f32_32x32x16_bf16(F0, qf[0], negm, 0, 0, 0); ADD4(pa, 0); pw[0][0] = cvtpk(pa[0], pa[1]); SB();
;         F0 = FLOAD(3); s1 = __builtin_amdgcn_mfma_f32_32x32x16_bf16(F1, qf[0], negm, 0, 0, 0); ADD4(pa, 4); pw[0][1] = cvtpk(pa[2], pa[3]); SB();
;         F1 = FLOAD(4); s0 = __builtin_amdgcn_mfma_f32_32x32x16_bf16(F2, qf[1], s0, 0, 0, 0); ADD4(pa, 8); pw[0][2] = cvtpk(pa[4], pa[5]); SB();
;         F2 = FLOAD(5); s1 = __builtin_amdgcn_mfma_f32_32x32x16_bf16(F0, qf[1], s1, 0, 0, 0); ADD4(pa, 12); pw[0][3] = cvtpk(pa[6], pa[7]); SB();
;         F0 = FLOAD(6); s0 = __builtin_amdgcn_mfma_f32_32x32x16_bf16(F1, qf[2], s0, 0, 0, 0); ADD4(pb, 0); pw[1][0] = cvtpk(pa[8], pa[9]); SB();
;         F1 = FLOAD(7); s1 = __builtin_amdgcn_mfma_f32_32x32x16_bf16(F2, qf[2], s1, 0, 0, 0); ADD4(pb, 4); pw[1][1] = cvtpk(pa[10], pa[11]); SB();
;         F2 = FLOAD(8); s0 = __builtin_amdgcn_mfma_f32_32x32x16_bf16(F0, qf[3], s0, 0, 0, 0); ADD4(pb, 8); pw[1][2] = cvtpk(pa[12], pa[13]); SB();
;         F0 = FLOAD(9); s1 = __builtin_amdgcn_mfma_f32_32x32x16_bf16(F1, qf[3], s1, 0, 0, 0); ADD4(pb, 12); pw[1][3] = cvtpk(pa[14], pa[15]); SB();
;         F1 = FLOAD(10); o[0] = __builtin_amdgcn_mfma_f32_32x32x16_bf16(F2, __builtin_bit_cast(bf16x8, pw[0]), o[0], 0, 0, 0); pw[2][0] = cvtpk(pb[0], pb[1]); EXP2(s0, pa, 0); SB();
;         F2 = FLOAD(11); o[1] = __builtin_amdgcn_mfma_f32_32x32x16_bf16(F0, __builtin_bit_cast(bf16x8, pw[0]), o[1], 0, 0, 0); pw[2][1] = cvtpk(pb[2], pb[3]); EXP2(s0, pa, 2); SB();
;         F0 = FLOAD(12); o[2] = __builtin_amdgcn_mfma_f32_32x32x16_bf16(F1, __builtin_bit_cast(bf16x8, pw[0]), o[2], 0, 0, 0); pw[2][2] = cvtpk(pb[4], pb[5]); EXP2(s0, pa, 4); SB();
;         F1 = FLOAD(13); o[3] = __builtin_amdgcn_mfma_f32_32x32x16_bf16(F2, __builtin_bit_cast(bf16x8, pw[0]), o[3], 0, 0, 0); pw[2][3] = cvtpk(pb[6], pb[7]); EXP2(s0, pa, 6); SB();
;         F2 = FLOAD(14); o[0] = __builtin_amdgcn_mfma_f32_32x32x16_bf16(F0, __builtin_bit_cast(bf16x8, pw[1]), o[0], 0, 0, 0); pw[3][0] = cvtpk(pb[8], pb[9]); EXP2(s0, pa, 8); SB();
	v_mfma_f32_16x16x32_bf16 v[64:67], v[4:7], v[228:231], v[64:67]
	ds_read_b128 v[224:227], v202 offset:22528
	v_exp_f32_e32 v203, v96
	v_mfma_f32_16x16x32_bf16 v[68:71], v[4:7], v[240:243], v[68:71]
	v_exp_f32_e32 v204, v97
	v_mfma_f32_16x16x32_bf16 v[72:75], v[8:11], v[228:231], v[72:75]
	ds_read_b128 v[4:7], v202 offset:24576
	v_exp_f32_e32 v205, v98
	v_mfma_f32_16x16x32_bf16 v[76:79], v[8:11], v[240:243], v[76:79]
	v_exp_f32_e32 v206, v99
	s_waitcnt lgkmcnt(1)
	v_mfma_f32_16x16x32_bf16 v[48:51], v[12:15], v[228:231], v[48:51]
	ds_read_b128 v[8:11], v202 offset:26624
	v_exp_f32_e32 v207, v100
	v_mfma_f32_16x16x32_bf16 v[52:55], v[12:15], v[240:243], v[52:55]
	v_exp_f32_e32 v208, v101
	v_mfma_f32_16x16x32_bf16 v[56:59], v[224:227], v[228:231], v[56:59]
	ds_read_b128 v[12:15], v202 offset:28672
	v_exp_f32_e32 v209, v102
	v_mfma_f32_16x16x32_bf16 v[60:63], v[224:227], v[240:243], v[60:63]
	v_exp_f32_e32 v210, v103
	s_waitcnt lgkmcnt(1)
	v_mfma_f32_16x16x32_bf16 v[32:35], v[4:7], v[228:231], v[32:35]
	ds_read_b128 v[224:227], v202 offset:30720
	v_exp_f32_e32 v211, v104
	v_mfma_f32_16x16x32_bf16 v[36:39], v[4:7], v[240:243], v[36:39]
	v_exp_f32_e32 v213, v105
	v_mfma_f32_16x16x32_bf16 v[40:43], v[8:11], v[228:231], v[40:43]
	ds_read_b128 v[4:7], v247
	v_exp_f32_e32 v214, v106
	v_mfma_f32_16x16x32_bf16 v[44:47], v[8:11], v[240:243], v[44:47]
	v_exp_f32_e32 v215, v107
	s_waitcnt lgkmcnt(1)
	v_mfma_f32_16x16x32_bf16 v[16:19], v[12:15], v[228:231], v[16:19]
	ds_read_b128 v[8:11], v248
	v_exp_f32_e32 v216, v108
	v_mfma_f32_16x16x32_bf16 v[20:23], v[12:15], v[240:243], v[20:23]
	v_exp_f32_e32 v217, v109
	v_mfma_f32_16x16x32_bf16 v[24:27], v[224:227], v[228:231], v[24:27]
	ds_read_b128 v[12:15], v247 offset:2048
	v_exp_f32_e32 v218, v110
	v_mfma_f32_16x16x32_bf16 v[28:31], v[224:227], v[240:243], v[28:31]
	v_exp_f32_e32 v219, v111
	s_add_i32 s33, s33, 1
.Lattn_c2:
	s_waitcnt lgkmcnt(1)
	v_mfma_f32_16x16x32_bf16 v[80:83], v[4:7], v[112:115], v[0:3]
	ds_read_b128 v[224:227], v248 offset:2048
	v_add_f32_e32 v222, v222, v183
	v_add_f32_e32 v223, v223, v187
	v_cvt_pk_bf16_f32 v232, v183, v184
	v_mfma_f32_16x16x32_bf16 v[84:87], v[4:7], v[120:123], v[0:3]
	v_add_f32_e32 v222, v222, v184
	v_add_f32_e32 v223, v223, v188
	v_mfma_f32_16x16x32_bf16 v[80:83], v[8:11], v[116:119], v[80:83]
	ds_read_b128 v[4:7], v247 offset:8192
	v_add_f32_e32 v222, v222, v185
	v_add_f32_e32 v223, v223, v189
	v_cvt_pk_bf16_f32 v233, v185, v186
	v_mfma_f32_16x16x32_bf16 v[84:87], v[8:11], v[124:127], v[84:87]
	v_add_f32_e32 v222, v222, v186
	v_add_f32_e32 v223, v223, v190
	s_waitcnt lgkmcnt(1)
	v_mfma_f32_16x16x32_bf16 v[88:91], v[12:15], v[112:115], v[0:3]
	ds_read_b128 v[8:11], v248 offset:8192
	v_add_f32_e32 v222, v222, v191
	v_add_f32_e32 v223, v223, v195
	v_cvt_pk_bf16_f32 v234, v191, v192
	v_mfma_f32_16x16x32_bf16 v[92:95], v[12:15], v[120:123], v[0:3]
	v_add_f32_e32 v222, v222, v192
	v_add_f32_e32 v223, v223, v196
	v_mfma_f32_16x16x32_bf16 v[88:91], v[224:227], v[116:119], v[88:91]
	ds_read_b128 v[12:15], v247 offset:10240
	v_add_f32_e32 v222, v222, v193
	v_add_f32_e32 v223, v223, v197
	v_cvt_pk_bf16_f32 v235, v193, v194
	v_mfma_f32_16x16x32_bf16 v[92:95], v[224:227], v[124:127], v[92:95]
	v_add_f32_e32 v222, v222, v194
	v_add_f32_e32 v223, v223, v199
	s_waitcnt lgkmcnt(1)
	v_mfma_f32_16x16x32_bf16 v[96:99], v[4:7], v[112:115], v[0:3]
	ds_read_b128 v[224:227], v248 offset:10240
	v_add_f32_e32 v222, v222, v203
	v_add_f32_e32 v223, v223, v207
	v_cvt_pk_bf16_f32 v236, v187, v188
	v_mfma_f32_16x16x32_bf16 v[100:103], v[4:7], v[120:123], v[0:3]
	v_add_f32_e32 v222, v222, v204
	v_add_f32_e32 v223, v223, v208
	v_mfma_f32_16x16x32_bf16 v[96:99], v[8:11], v[116:119], v[96:99]
	ds_read_b128 v[4:7], v201 offset:49152
	v_add_f32_e32 v222, v222, v205
	v_add_f32_e32 v223, v223, v209
	v_cvt_pk_bf16_f32 v237, v189, v190
	v_mfma_f32_16x16x32_bf16 v[100:103], v[8:11], v[124:127], v[100:103]
	v_add_f32_e32 v222, v222, v206
	v_add_f32_e32 v223, v223, v210
	s_waitcnt lgkmcnt(1)
	v_mfma_f32_16x16x32_bf16 v[104:107], v[12:15], v[112:115], v[0:3]
	ds_read_b128 v[8:11], v201 offset:51200
	v_add_f32_e32 v222, v222, v211
	v_add_f32_e32 v223, v223, v216
	v_cvt_pk_bf16_f32 v238, v195, v196
	v_mfma_f32_16x16x32_bf16 v[108:111], v[12:15], v[120:123], v[0:3]
	v_add_f32_e32 v222, v222, v213
	v_add_f32_e32 v223, v223, v217
	v_mfma_f32_16x16x32_bf16 v[104:107], v[224:227], v[116:119], v[104:107]
	ds_read_b128 v[12:15], v201 offset:53248
	v_add_f32_e32 v222, v222, v214
	v_add_f32_e32 v223, v223, v218
	v_cvt_pk_bf16_f32 v239, v197, v199
	v_mfma_f32_16x16x32_bf16 v[108:111], v[224:227], v[124:127], v[108:111]
	v_add_f32_e32 v222, v222, v215
	v_add_f32_e32 v223, v223, v219
	s_waitcnt vmcnt(0)
	s_barrier
; __device__ __forceinline__ void attn_unit(unsigned char* ws, const float* sub_g, LAS unsigned char* lds, int h, int qb, float negM, float lam) {
;     ...
;         F1 = FLOAD(10); o[0] = __builtin_amdgcn_mfma_f32_32x32x16_bf16(F2, __builtin_bit_cast(bf16x8, pw[0]), o[0], 0, 0, 0); pw[2][0] = cvtpk(pb[0], pb[1]); EXP2(s0, pa, 0); SB();
;         F2 = FLOAD(11); o[1] = __builtin_amdgcn_mfma_f32_32x32x16_bf16(F0, __builtin_bit_cast(bf16x8, pw[0]), o[1], 0, 0, 0); pw[2][1] = cvtpk(pb[2], pb[3]); EXP2(s0, pa, 2); SB();
;         F0 = FLOAD(12); o[2] = __builtin_amdgcn_mfma_f32_32x32x16_bf16(F1, __builtin_bit_cast(bf16x8, pw[0]), o[2], 0, 0, 0); pw[2][2] = cvtpk(pb[4], pb[5]); EXP2(s0, pa, 4); SB();
;         F1 = FLOAD(13); o[3] = __builtin_amdgcn_mfma_f32_32x32x16_bf16(F2, __builtin_bit_cast(bf16x8, pw[0]), o[3], 0, 0, 0); pw[2][3] = cvtpk(pb[6], pb[7]); EXP2(s0, pa, 6); SB();
;         F2 = FLOAD(14); o[0] = __builtin_amdgcn_mfma_f32_32x32x16_bf16(F0, __builtin_bit_cast(bf16x8, pw[1]), o[0], 0, 0, 0); pw[3][0] = cvtpk(pb[8], pb[9]); EXP2(s0, pa, 8); SB();
;         F0 = FLOAD(15); o[1] = __builtin_amdgcn_mfma_f32_32x32x16_bf16(F1, __builtin_bit_cast(bf16x8, pw[1]), o[1], 0, 0, 0); pw[3][1] = cvtpk(pb[10], pb[11]); EXP2(s0, pa, 10); SB();
;         F1 = FLOAD(16); o[2] = __builtin_amdgcn_mfma_f32_32x32x16_bf16(F2, __builtin_bit_cast(bf16x8, pw[1]), o[2], 0, 0, 0); pw[3][2] = cvtpk(pb[12], pb[13]); EXP2(s0, pa, 12); SB();
;         F2 = FLOAD(17); o[3] = __builtin_amdgcn_mfma_f32_32x32x16_bf16(F0, __builtin_bit_cast(bf16x8, pw[1]), o[3], 0, 0, 0); pw[3][3] = cvtpk(pb[14], pb[15]); EXP2(s0, pa, 14); SB();
;         F0 = FLOAD(18); o[0] = __builtin_amdgcn_mfma_f32_32x32x16_bf16(F1, __builtin_bit_cast(bf16x8, pw[2]), o[0], 0, 0, 0); EXP2(s1, pb, 0); SB();
;         F1 = FLOAD(19); o[1] = __builtin_amdgcn_mfma_f32_32x32x16_bf16(F2, __builtin_bit_cast(bf16x8, pw[2]), o[1], 0, 0, 0); EXP2(s1, pb, 2); SB();
;         F2 = FLOAD(20); o[2] = __builtin_amdgcn_mfma_f32_32x32x16_bf16(F0, __builtin_bit_cast(bf16x8, pw[2]), o[2], 0, 0, 0); EXP2(s1, pb, 4); SB();
;         F0 = FLOAD(21); o[3] = __builtin_amdgcn_mfma_f32_32x32x16_bf16(F1, __builtin_bit_cast(bf16x8, pw[2]), o[3], 0, 0, 0); EXP2(s1, pb, 6); SB();
;         F1 = FLOAD(22); o[0] = __builtin_amdgcn_mfma_f32_32x32x16_bf16(F2, __builtin_bit_cast(bf16x8, pw[3]), o[0], 0, 0, 0); EXP2(s1, pb, 8); SB();
	s_waitcnt lgkmcnt(1)
	v_mfma_f32_16x16x32_bf16 v[64:67], v[4:7], v[232:235], v[64:67]
	s_add_i32 m0, s8, 0x0
	ds_read_b128 v[224:227], v201 offset:55296
	global_load_lds_dwordx4 v140, s[98:99]
	v_exp_f32_e32 v183, v80
	v_cvt_pk_bf16_f32 v228, v203, v204
	v_mfma_f32_16x16x32_bf16 v[68:71], v[4:7], v[236:239], v[68:71]
	v_exp_f32_e32 v184, v81
	v_mfma_f32_16x16x32_bf16 v[72:75], v[8:11], v[232:235], v[72:75]
	s_add_i32 m0, m0, 0x4000
	ds_read_b128 v[4:7], v201 offset:57344
	global_load_lds_dwordx4 v144, s[100:101]
	v_exp_f32_e32 v185, v82
	v_cvt_pk_bf16_f32 v229, v205, v206
	v_mfma_f32_16x16x32_bf16 v[76:79], v[8:11], v[236:239], v[76:79]
	v_exp_f32_e32 v186, v83
	s_waitcnt lgkmcnt(1)
	v_mfma_f32_16x16x32_bf16 v[48:51], v[12:15], v[232:235], v[48:51]
	s_add_i32 m0, m0, 0xffffc400
	ds_read_b128 v[8:11], v201 offset:59392
	global_load_lds_dwordx4 v142, s[98:99]
	v_exp_f32_e32 v187, v84
	v_cvt_pk_bf16_f32 v230, v211, v213
	v_mfma_f32_16x16x32_bf16 v[52:55], v[12:15], v[236:239], v[52:55]
	v_exp_f32_e32 v188, v85
	v_mfma_f32_16x16x32_bf16 v[56:59], v[224:227], v[232:235], v[56:59]
	s_add_i32 m0, m0, 0x4000
	ds_read_b128 v[12:15], v201 offset:61440
	global_load_lds_dwordx4 v146, s[100:101]
	s_add_u32 s98, s98, 0x20000
	s_addc_u32 s99, s99, 0
	s_add_u32 s100, s100, 0x80
	s_addc_u32 s101, s101, 0
	v_exp_f32_e32 v189, v86
	v_cvt_pk_bf16_f32 v231, v214, v215
	v_mfma_f32_16x16x32_bf16 v[60:63], v[224:227], v[236:239], v[60:63]
	v_exp_f32_e32 v190, v87
	s_waitcnt lgkmcnt(1)
	v_mfma_f32_16x16x32_bf16 v[32:35], v[4:7], v[232:235], v[32:35]
	ds_read_b128 v[224:227], v201 offset:63488
	v_exp_f32_e32 v191, v88
	v_cvt_pk_bf16_f32 v240, v207, v208
	v_mfma_f32_16x16x32_bf16 v[36:39], v[4:7], v[236:239], v[36:39]
	v_exp_f32_e32 v192, v89
	v_mfma_f32_16x16x32_bf16 v[40:43], v[8:11], v[232:235], v[40:43]
	ds_read_b128 v[4:7], v202 offset:49152
	v_exp_f32_e32 v193, v90
	v_cvt_pk_bf16_f32 v241, v209, v210
	v_mfma_f32_16x16x32_bf16 v[44:47], v[8:11], v[236:239], v[44:47]
	v_exp_f32_e32 v194, v91
	s_waitcnt lgkmcnt(1)
	v_mfma_f32_16x16x32_bf16 v[16:19], v[12:15], v[232:235], v[16:19]
	ds_read_b128 v[8:11], v202 offset:51200
	v_exp_f32_e32 v195, v92
	v_cvt_pk_bf16_f32 v242, v216, v217
	v_mfma_f32_16x16x32_bf16 v[20:23], v[12:15], v[236:239], v[20:23]
	v_exp_f32_e32 v196, v93
	v_mfma_f32_16x16x32_bf16 v[24:27], v[224:227], v[232:235], v[24:27]
	ds_read_b128 v[12:15], v202 offset:53248
	v_exp_f32_e32 v197, v94
	v_cvt_pk_bf16_f32 v243, v218, v219
	v_mfma_f32_16x16x32_bf16 v[28:31], v[224:227], v[236:239], v[28:31]
	v_exp_f32_e32 v199, v95
	s_waitcnt lgkmcnt(1)
	v_mfma_f32_16x16x32_bf16 v[64:67], v[4:7], v[228:231], v[64:67]
	ds_read_b128 v[224:227], v202 offset:55296
	v_exp_f32_e32 v203, v96
	v_mfma_f32_16x16x32_bf16 v[68:71], v[4:7], v[240:243], v[68:71]
	v_exp_f32_e32 v204, v97
	v_mfma_f32_16x16x32_bf16 v[72:75], v[8:11], v[228:231], v[72:75]
	ds_read_b128 v[4:7], v202 offset:57344
	v_exp_f32_e32 v205, v98
	v_mfma_f32_16x16x32_bf16 v[76:79], v[8:11], v[240:243], v[76:79]
	v_exp_f32_e32 v206, v99
	s_waitcnt lgkmcnt(1)
	v_mfma_f32_16x16x32_bf16 v[48:51], v[12:15], v[228:231], v[48:51]
	ds_read_b128 v[8:11], v202 offset:59392
	v_exp_f32_e32 v207, v100
	v_mfma_f32_16x16x32_bf16 v[52:55], v[12:15], v[240:243], v[52:55]
	v_exp_f32_e32 v208, v101
	v_mfma_f32_16x16x32_bf16 v[56:59], v[224:227], v[228:231], v[56:59]
	ds_read_b128 v[12:15], v202 offset:61440
	v_exp_f32_e32 v209, v102
	v_mfma_f32_16x16x32_bf16 v[60:63], v[224:227], v[240:243], v[60:63]
	v_exp_f32_e32 v210, v103
	s_waitcnt lgkmcnt(1)
	v_mfma_f32_16x16x32_bf16 v[32:35], v[4:7], v[228:231], v[32:35]
	ds_read_b128 v[224:227], v202 offset:63488
	v_exp_f32_e32 v211, v104
	v_mfma_f32_16x16x32_bf16 v[36:39], v[4:7], v[240:243], v[36:39]
	v_exp_f32_e32 v213, v105
	v_mfma_f32_16x16x32_bf16 v[40:43], v[8:11], v[228:231], v[40:43]
	ds_read_b128 v[4:7], v247 offset:32768
	v_exp_f32_e32 v214, v106
	v_mfma_f32_16x16x32_bf16 v[44:47], v[8:11], v[240:243], v[44:47]
	v_exp_f32_e32 v215, v107
	s_waitcnt lgkmcnt(1)
	v_mfma_f32_16x16x32_bf16 v[16:19], v[12:15], v[228:231], v[16:19]
	ds_read_b128 v[8:11], v248 offset:32768
	v_exp_f32_e32 v216, v108
	v_mfma_f32_16x16x32_bf16 v[20:23], v[12:15], v[240:243], v[20:23]
	v_exp_f32_e32 v217, v109
	v_mfma_f32_16x16x32_bf16 v[24:27], v[224:227], v[228:231], v[24:27]
	ds_read_b128 v[12:15], v247 offset:34816
	v_exp_f32_e32 v218, v110
	v_mfma_f32_16x16x32_bf16 v[28:31], v[224:227], v[240:243], v[28:31]
	v_exp_f32_e32 v219, v111
	s_add_i32 s33, s33, 1
; #define SB() __builtin_amdgcn_sched_barrier(0)
; __device__ __forceinline__ void attn_unit(unsigned char* ws, const float* sub_g, LAS unsigned char* lds, int h, int qb, float negM, float lam) {
;     ...
;         bf16x8 F0 = FLOAD(0), F1 = FLOAD(1), F2;
;         SB();
;         F2 = FLOAD(2); s0 = __builtin_amdgcn_mfma_f32_32x32x16_bf16(F0, qf[0], negm, 0, 0, 0); ADD4(pa, 0); pw[0][0] = cvtpk(pa[0], pa[1]); SB();
;         F0 = FLOAD(3); s1 = __builtin_amdgcn_mfma_f32_32x32x16_bf16(F1, qf[0], negm, 0, 0, 0); ADD4(pa, 4); pw[0][1] = cvtpk(pa[2], pa[3]); SB();
;         F1 = FLOAD(4); s0 = __builtin_amdgcn_mfma_f32_32x32x16_bf16(F2, qf[1], s0, 0, 0, 0); ADD4(pa, 8); pw[0][2] = cvtpk(pa[4], pa[5]); SB();
;         F2 = FLOAD(5); s1 = __builtin_amdgcn_mfma_f32_32x32x16_bf16(F0, qf[1], s1, 0, 0, 0); ADD4(pa, 12); pw[0][3] = cvtpk(pa[6], pa[7]); SB();
;         F0 = FLOAD(6); s0 = __builtin_amdgcn_mfma_f32_32x32x16_bf16(F1, qf[2], s0, 0, 0, 0); ADD4(pb, 0); pw[1][0] = cvtpk(pa[8], pa[9]); SB();
;         F1 = FLOAD(7); s1 = __builtin_amdgcn_mfma_f32_32x32x16_bf16(F2, qf[2], s1, 0, 0, 0); ADD4(pb, 4); pw[1][1] = cvtpk(pa[10], pa[11]); SB();
;         F2 = FLOAD(8); s0 = __builtin_amdgcn_mfma_f32_32x32x16_bf16(F0, qf[3], s0, 0, 0, 0); ADD4(pb, 8); pw[1][2] = cvtpk(pa[12], pa[13]); SB();
;         F0 = FLOAD(9); s1 = __builtin_amdgcn_mfma_f32_32x32x16_bf16(F1, qf[3], s1, 0, 0, 0); ADD4(pb, 12); pw[1][3] = cvtpk(pa[14], pa[15]); SB();
;         F1 = FLOAD(10); o[0] = __builtin_amdgcn_mfma_f32_32x32x16_bf16(F2, __builtin_bit_cast(bf16x8, pw[0]), o[0], 0, 0, 0); pw[2][0] = cvtpk(pb[0], pb[1]); EXP2(s0, pa, 0); SB();
;         F2 = FLOAD(11); o[1] = __builtin_amdgcn_mfma_f32_32x32x16_bf16(F0, __builtin_bit_cast(bf16x8, pw[0]), o[1], 0, 0, 0); pw[2][1] = cvtpk(pb[2], pb[3]); EXP2(s0, pa, 2); SB();
;         F0 = FLOAD(12); o[2] = __builtin_amdgcn_mfma_f32_32x32x16_bf16(F1, __builtin_bit_cast(bf16x8, pw[0]), o[2], 0, 0, 0); pw[2][2] = cvtpk(pb[4], pb[5]); EXP2(s0, pa, 4); SB();
;         F1 = FLOAD(13); o[3] = __builtin_amdgcn_mfma_f32_32x32x16_bf16(F2, __builtin_bit_cast(bf16x8, pw[0]), o[3], 0, 0, 0); pw[2][3] = cvtpk(pb[6], pb[7]); EXP2(s0, pa, 6); SB();
;         F2 = FLOAD(14); o[0] = __builtin_amdgcn_mfma_f32_32x32x16_bf16(F0, __builtin_bit_cast(bf16x8, pw[1]), o[0], 0, 0, 0); pw[3][0] = cvtpk(pb[8], pb[9]); EXP2(s0, pa, 8); SB();
.Lattn_c3:
	s_waitcnt lgkmcnt(1)
	v_mfma_f32_16x16x32_bf16 v[80:83], v[4:7], v[112:115], v[0:3]
	ds_read_b128 v[224:227], v248 offset:34816
	v_add_f32_e32 v222, v222, v183
	v_add_f32_e32 v223, v223, v187
	v_cvt_pk_bf16_f32 v232, v183, v184
	v_mfma_f32_16x16x32_bf16 v[84:87], v[4:7], v[120:123], v[0:3]
	v_add_f32_e32 v222, v222, v184
	v_add_f32_e32 v223, v223, v188
	v_mfma_f32_16x16x32_bf16 v[80:83], v[8:11], v[116:119], v[80:83]
	ds_read_b128 v[4:7], v247 offset:40960
	v_add_f32_e32 v222, v222, v185
	v_add_f32_e32 v223, v223, v189
	v_cvt_pk_bf16_f32 v233, v185, v186
	v_mfma_f32_16x16x32_bf16 v[84:87], v[8:11], v[124:127], v[84:87]
	v_add_f32_e32 v222, v222, v186
	v_add_f32_e32 v223, v223, v190
	s_waitcnt lgkmcnt(1)
	v_mfma_f32_16x16x32_bf16 v[88:91], v[12:15], v[112:115], v[0:3]
	ds_read_b128 v[8:11], v248 offset:40960
	v_add_f32_e32 v222, v222, v191
	v_add_f32_e32 v223, v223, v195
	v_cvt_pk_bf16_f32 v234, v191, v192
	v_mfma_f32_16x16x32_bf16 v[92:95], v[12:15], v[120:123], v[0:3]
	v_add_f32_e32 v222, v222, v192
	v_add_f32_e32 v223, v223, v196
	v_mfma_f32_16x16x32_bf16 v[88:91], v[224:227], v[116:119], v[88:91]
	ds_read_b128 v[12:15], v247 offset:43008
	v_add_f32_e32 v222, v222, v193
	v_add_f32_e32 v223, v223, v197
	v_cvt_pk_bf16_f32 v235, v193, v194
	v_mfma_f32_16x16x32_bf16 v[92:95], v[224:227], v[124:127], v[92:95]
	v_add_f32_e32 v222, v222, v194
	v_add_f32_e32 v223, v223, v199
	s_waitcnt lgkmcnt(1)
	v_mfma_f32_16x16x32_bf16 v[96:99], v[4:7], v[112:115], v[0:3]
	ds_read_b128 v[224:227], v248 offset:43008
	v_add_f32_e32 v222, v222, v203
	v_add_f32_e32 v223, v223, v207
	v_cvt_pk_bf16_f32 v236, v187, v188
	v_mfma_f32_16x16x32_bf16 v[100:103], v[4:7], v[120:123], v[0:3]
	v_add_f32_e32 v222, v222, v204
	v_add_f32_e32 v223, v223, v208
	v_mfma_f32_16x16x32_bf16 v[96:99], v[8:11], v[116:119], v[96:99]
	ds_read_b128 v[4:7], v249 offset:16384
	v_add_f32_e32 v222, v222, v205
	v_add_f32_e32 v223, v223, v209
	v_cvt_pk_bf16_f32 v237, v189, v190
	v_mfma_f32_16x16x32_bf16 v[100:103], v[8:11], v[124:127], v[100:103]
	v_add_f32_e32 v222, v222, v206
	v_add_f32_e32 v223, v223, v210
	s_waitcnt lgkmcnt(1)
	v_mfma_f32_16x16x32_bf16 v[104:107], v[12:15], v[112:115], v[0:3]
	ds_read_b128 v[8:11], v249 offset:18432
	v_add_f32_e32 v222, v222, v211
	v_add_f32_e32 v223, v223, v216
	v_cvt_pk_bf16_f32 v238, v195, v196
	v_mfma_f32_16x16x32_bf16 v[108:111], v[12:15], v[120:123], v[0:3]
	v_add_f32_e32 v222, v222, v213
	v_add_f32_e32 v223, v223, v217
	v_mfma_f32_16x16x32_bf16 v[104:107], v[224:227], v[116:119], v[104:107]
	ds_read_b128 v[12:15], v249 offset:20480
	v_add_f32_e32 v222, v222, v214
	v_add_f32_e32 v223, v223, v218
	v_cvt_pk_bf16_f32 v239, v197, v199
	v_mfma_f32_16x16x32_bf16 v[108:111], v[224:227], v[124:127], v[108:111]
	v_add_f32_e32 v222, v222, v215
	v_add_f32_e32 v223, v223, v219
	s_waitcnt vmcnt(0)
	s_barrier
	s_waitcnt lgkmcnt(1)
	v_mfma_f32_16x16x32_bf16 v[64:67], v[4:7], v[232:235], v[64:67]
	s_add_i32 m0, s8, 0x8000
	ds_read_b128 v[224:227], v249 offset:22528
	global_load_lds_dwordx4 v140, s[98:99]
	v_exp_f32_e32 v183, v80
	v_cvt_pk_bf16_f32 v228, v203, v204
	v_mfma_f32_16x16x32_bf16 v[68:71], v[4:7], v[236:239], v[68:71]
	v_exp_f32_e32 v184, v81
	v_mfma_f32_16x16x32_bf16 v[72:75], v[8:11], v[232:235], v[72:75]
	s_add_i32 m0, m0, 0x4000
	ds_read_b128 v[4:7], v249 offset:24576
	global_load_lds_dwordx4 v144, s[100:101]
	v_exp_f32_e32 v185, v82
	v_cvt_pk_bf16_f32 v229, v205, v206
	v_mfma_f32_16x16x32_bf16 v[76:79], v[8:11], v[236:239], v[76:79]
	v_exp_f32_e32 v186, v83
	s_waitcnt lgkmcnt(1)
	v_mfma_f32_16x16x32_bf16 v[48:51], v[12:15], v[232:235], v[48:51]
	s_add_i32 m0, m0, 0xffffc400
	ds_read_b128 v[8:11], v249 offset:26624
	global_load_lds_dwordx4 v142, s[98:99]
	v_exp_f32_e32 v187, v84
	v_cvt_pk_bf16_f32 v230, v211, v213
	v_mfma_f32_16x16x32_bf16 v[52:55], v[12:15], v[236:239], v[52:55]
	v_exp_f32_e32 v188, v85
	v_mfma_f32_16x16x32_bf16 v[56:59], v[224:227], v[232:235], v[56:59]
	s_add_i32 m0, m0, 0x4000
	ds_read_b128 v[12:15], v249 offset:28672
	global_load_lds_dwordx4 v146, s[100:101]
	s_add_u32 s98, s98, 0x20000
	s_addc_u32 s99, s99, 0
	s_add_u32 s100, s100, 0x80
	s_addc_u32 s101, s101, 0
	v_exp_f32_e32 v189, v86
	v_cvt_pk_bf16_f32 v231, v214, v215
	v_mfma_f32_16x16x32_bf16 v[60:63], v[224:227], v[236:239], v[60:63]
	v_exp_f32_e32 v190, v87
	s_waitcnt lgkmcnt(1)
	v_mfma_f32_16x16x32_bf16 v[32:35], v[4:7], v[232:235], v[32:35]
	ds_read_b128 v[224:227], v249 offset:30720
	v_exp_f32_e32 v191, v88
	v_cvt_pk_bf16_f32 v240, v207, v208
	v_mfma_f32_16x16x32_bf16 v[36:39], v[4:7], v[236:239], v[36:39]
	v_exp_f32_e32 v192, v89
	v_mfma_f32_16x16x32_bf16 v[40:43], v[8:11], v[232:235], v[40:43]
	ds_read_b128 v[4:7], v250 offset:16384
	v_exp_f32_e32 v193, v90
	v_cvt_pk_bf16_f32 v241, v209, v210
	v_mfma_f32_16x16x32_bf16 v[44:47], v[8:11], v[236:239], v[44:47]
	v_exp_f32_e32 v194, v91
	s_waitcnt lgkmcnt(1)
	v_mfma_f32_16x16x32_bf16 v[16:19], v[12:15], v[232:235], v[16:19]
	ds_read_b128 v[8:11], v250 offset:18432
	v_exp_f32_e32 v195, v92
	v_cvt_pk_bf16_f32 v242, v216, v217
	v_mfma_f32_16x16x32_bf16 v[20:23], v[12:15], v[236:239], v[20:23]
	v_exp_f32_e32 v196, v93
	v_mfma_f32_16x16x32_bf16 v[24:27], v[224:227], v[232:235], v[24:27]
	ds_read_b128 v[12:15], v250 offset:20480
	v_exp_f32_e32 v197, v94
	v_cvt_pk_bf16_f32 v243, v218, v219
	v_mfma_f32_16x16x32_bf16 v[28:31], v[224:227], v[236:239], v[28:31]
	v_exp_f32_e32 v199, v95
	s_waitcnt lgkmcnt(1)
; #define SB() __builtin_amdgcn_sched_barrier(0)
; __device__ __forceinline__ void attn_unit(unsigned char* ws, const float* sub_g, LAS unsigned char* lds, int h, int qb, float negM, float lam) {
;     ...
;         bf16x8 F0 = FLOAD(0), F1 = FLOAD(1), F2;
;         SB();
;         F2 = FLOAD(2); s0 = __builtin_amdgcn_mfma_f32_32x32x16_bf16(F0, qf[0], negm, 0, 0, 0); ADD4(pa, 0); pw[0][0] = cvtpk(pa[0], pa[1]); SB();
;         F0 = FLOAD(3); s1 = __builtin_amdgcn_mfma_f32_32x32x16_bf16(F1, qf[0], negm, 0, 0, 0); ADD4(pa, 4); pw[0][1] = cvtpk(pa[2], pa[3]); SB();
;         F1 = FLOAD(4); s0 = __builtin_amdgcn_mfma_f32_32x32x16_bf16(F2, qf[1], s0, 0, 0, 0); ADD4(pa, 8); pw[0][2] = cvtpk(pa[4], pa[5]); SB();
;         F2 = FLOAD(5); s1 = __builtin_amdgcn_mfma_f32_32x32x16_bf16(F0, qf[1], s1, 0, 0, 0); ADD4(pa, 12); pw[0][3] = cvtpk(pa[6], pa[7]); SB();
;         F0 = FLOAD(6); s0 = __builtin_amdgcn_mfma_f32_32x32x16_bf16(F1, qf[2], s0, 0, 0, 0); ADD4(pb, 0); pw[1][0] = cvtpk(pa[8], pa[9]); SB();
;         F1 = FLOAD(7); s1 = __builtin_amdgcn_mfma_f32_32x32x16_bf16(F2, qf[2], s1, 0, 0, 0); ADD4(pb, 4); pw[1][1] = cvtpk(pa[10], pa[11]); SB();
;         F2 = FLOAD(8); s0 = __builtin_amdgcn_mfma_f32_32x32x16_bf16(F0, qf[3], s0, 0, 0, 0); ADD4(pb, 8); pw[1][2] = cvtpk(pa[12], pa[13]); SB();
;         F0 = FLOAD(9); s1 = __builtin_amdgcn_mfma_f32_32x32x16_bf16(F1, qf[3], s1, 0, 0, 0); ADD4(pb, 12); pw[1][3] = cvtpk(pa[14], pa[15]); SB();
;         F1 = FLOAD(10); o[0] = __builtin_amdgcn_mfma_f32_32x32x16_bf16(F2, __builtin_bit_cast(bf16x8, pw[0]), o[0], 0, 0, 0); pw[2][0] = cvtpk(pb[0], pb[1]); EXP2(s0, pa, 0); SB();
;         F2 = FLOAD(11); o[1] = __builtin_amdgcn_mfma_f32_32x32x16_bf16(F0, __builtin_bit_cast(bf16x8, pw[0]), o[1], 0, 0, 0); pw[2][1] = cvtpk(pb[2], pb[3]); EXP2(s0, pa, 2); SB();
;         F0 = FLOAD(12); o[2] = __builtin_amdgcn_mfma_f32_32x32x16_bf16(F1, __builtin_bit_cast(bf16x8, pw[0]), o[2], 0, 0, 0); pw[2][2] = cvtpk(pb[4], pb[5]); EXP2(s0, pa, 4); SB();
;         F1 = FLOAD(13); o[3] = __builtin_amdgcn_mfma_f32_32x32x16_bf16(F2, __builtin_bit_cast(bf16x8, pw[0]), o[3], 0, 0, 0); pw[2][3] = cvtpk(pb[6], pb[7]); EXP2(s0, pa, 6); SB();
;         F2 = FLOAD(14); o[0] = __builtin_amdgcn_mfma_f32_32x32x16_bf16(F0, __builtin_bit_cast(bf16x8, pw[1]), o[0], 0, 0, 0); pw[3][0] = cvtpk(pb[8], pb[9]); EXP2(s0, pa, 8); SB();
	v_mfma_f32_16x16x32_bf16 v[64:67], v[4:7], v[228:231], v[64:67]
	ds_read_b128 v[224:227], v250 offset:22528
	v_exp_f32_e32 v203, v96
	v_mfma_f32_16x16x32_bf16 v[68:71], v[4:7], v[240:243], v[68:71]
	v_exp_f32_e32 v204, v97
	v_mfma_f32_16x16x32_bf16 v[72:75], v[8:11], v[228:231], v[72:75]
	ds_read_b128 v[4:7], v250 offset:24576
	v_exp_f32_e32 v205, v98
	v_mfma_f32_16x16x32_bf16 v[76:79], v[8:11], v[240:243], v[76:79]
	v_exp_f32_e32 v206, v99
	s_waitcnt lgkmcnt(1)
	v_mfma_f32_16x16x32_bf16 v[48:51], v[12:15], v[228:231], v[48:51]
	ds_read_b128 v[8:11], v250 offset:26624
	v_exp_f32_e32 v207, v100
	v_mfma_f32_16x16x32_bf16 v[52:55], v[12:15], v[240:243], v[52:55]
	v_exp_f32_e32 v208, v101
	v_mfma_f32_16x16x32_bf16 v[56:59], v[224:227], v[228:231], v[56:59]
	ds_read_b128 v[12:15], v250 offset:28672
	v_exp_f32_e32 v209, v102
	v_mfma_f32_16x16x32_bf16 v[60:63], v[224:227], v[240:243], v[60:63]
	v_exp_f32_e32 v210, v103
	s_waitcnt lgkmcnt(1)
	v_mfma_f32_16x16x32_bf16 v[32:35], v[4:7], v[228:231], v[32:35]
	ds_read_b128 v[224:227], v250 offset:30720
	v_exp_f32_e32 v211, v104
	v_mfma_f32_16x16x32_bf16 v[36:39], v[4:7], v[240:243], v[36:39]
	v_exp_f32_e32 v213, v105
	v_mfma_f32_16x16x32_bf16 v[40:43], v[8:11], v[228:231], v[40:43]
	ds_read_b128 v[4:7], v198
	v_exp_f32_e32 v214, v106
	v_mfma_f32_16x16x32_bf16 v[44:47], v[8:11], v[240:243], v[44:47]
	v_exp_f32_e32 v215, v107
	s_waitcnt lgkmcnt(1)
	v_mfma_f32_16x16x32_bf16 v[16:19], v[12:15], v[228:231], v[16:19]
	ds_read_b128 v[8:11], v200
	v_exp_f32_e32 v216, v108
	v_mfma_f32_16x16x32_bf16 v[20:23], v[12:15], v[240:243], v[20:23]
	v_exp_f32_e32 v217, v109
	v_mfma_f32_16x16x32_bf16 v[24:27], v[224:227], v[228:231], v[24:27]
	ds_read_b128 v[12:15], v198 offset:2048
	v_exp_f32_e32 v218, v110
	v_mfma_f32_16x16x32_bf16 v[28:31], v[224:227], v[240:243], v[28:31]
	v_exp_f32_e32 v219, v111
	s_add_i32 s33, s33, 1
	s_cmpk_eq_i32 s33, 0x84
	s_cbranch_scc1 .Lattn_exit
.Lattn_c0:
	s_waitcnt lgkmcnt(1)
	v_mfma_f32_16x16x32_bf16 v[80:83], v[4:7], v[112:115], v[0:3]
	ds_read_b128 v[224:227], v200 offset:2048
	v_add_f32_e32 v222, v222, v183
	v_add_f32_e32 v223, v223, v187
	v_cvt_pk_bf16_f32 v232, v183, v184
	v_mfma_f32_16x16x32_bf16 v[84:87], v[4:7], v[120:123], v[0:3]
	v_add_f32_e32 v222, v222, v184
	v_add_f32_e32 v223, v223, v188
	v_mfma_f32_16x16x32_bf16 v[80:83], v[8:11], v[116:119], v[80:83]
	ds_read_b128 v[4:7], v198 offset:8192
	v_add_f32_e32 v222, v222, v185
	v_add_f32_e32 v223, v223, v189
	v_cvt_pk_bf16_f32 v233, v185, v186
	v_mfma_f32_16x16x32_bf16 v[84:87], v[8:11], v[124:127], v[84:87]
	v_add_f32_e32 v222, v222, v186
	v_add_f32_e32 v223, v223, v190
	s_waitcnt lgkmcnt(1)
	v_mfma_f32_16x16x32_bf16 v[88:91], v[12:15], v[112:115], v[0:3]
	ds_read_b128 v[8:11], v200 offset:8192
	v_add_f32_e32 v222, v222, v191
	v_add_f32_e32 v223, v223, v195
	v_cvt_pk_bf16_f32 v234, v191, v192
	v_mfma_f32_16x16x32_bf16 v[92:95], v[12:15], v[120:123], v[0:3]
	v_add_f32_e32 v222, v222, v192
	v_add_f32_e32 v223, v223, v196
	v_mfma_f32_16x16x32_bf16 v[88:91], v[224:227], v[116:119], v[88:91]
	ds_read_b128 v[12:15], v198 offset:10240
	v_add_f32_e32 v222, v222, v193
	v_add_f32_e32 v223, v223, v197
	v_cvt_pk_bf16_f32 v235, v193, v194
	v_mfma_f32_16x16x32_bf16 v[92:95], v[224:227], v[124:127], v[92:95]
	v_add_f32_e32 v222, v222, v194
	v_add_f32_e32 v223, v223, v199
	s_waitcnt lgkmcnt(1)
	v_mfma_f32_16x16x32_bf16 v[96:99], v[4:7], v[112:115], v[0:3]
	ds_read_b128 v[224:227], v200 offset:10240
	v_add_f32_e32 v222, v222, v203
	v_add_f32_e32 v223, v223, v207
	v_cvt_pk_bf16_f32 v236, v187, v188
	v_mfma_f32_16x16x32_bf16 v[100:103], v[4:7], v[120:123], v[0:3]
	v_add_f32_e32 v222, v222, v204
	v_add_f32_e32 v223, v223, v208
	v_mfma_f32_16x16x32_bf16 v[96:99], v[8:11], v[116:119], v[96:99]
	ds_read_b128 v[4:7], v249 offset:49152
	v_add_f32_e32 v222, v222, v205
	v_add_f32_e32 v223, v223, v209
	v_cvt_pk_bf16_f32 v237, v189, v190
	v_mfma_f32_16x16x32_bf16 v[100:103], v[8:11], v[124:127], v[100:103]
	v_add_f32_e32 v222, v222, v206
	v_add_f32_e32 v223, v223, v210
	s_waitcnt lgkmcnt(1)
	v_mfma_f32_16x16x32_bf16 v[104:107], v[12:15], v[112:115], v[0:3]
	ds_read_b128 v[8:11], v249 offset:51200
	v_add_f32_e32 v222, v222, v211
	v_add_f32_e32 v223, v223, v216
	v_cvt_pk_bf16_f32 v238, v195, v196
	v_mfma_f32_16x16x32_bf16 v[108:111], v[12:15], v[120:123], v[0:3]
	v_add_f32_e32 v222, v222, v213
	v_add_f32_e32 v223, v223, v217
	v_mfma_f32_16x16x32_bf16 v[104:107], v[224:227], v[116:119], v[104:107]
	ds_read_b128 v[12:15], v249 offset:53248
	v_add_f32_e32 v222, v222, v214
	v_add_f32_e32 v223, v223, v218
	v_cvt_pk_bf16_f32 v239, v197, v199
	v_mfma_f32_16x16x32_bf16 v[108:111], v[224:227], v[124:127], v[108:111]
	v_add_f32_e32 v222, v222, v215
	v_add_f32_e32 v223, v223, v219
	s_waitcnt vmcnt(0)
	s_barrier
; __device__ __forceinline__ void attn_unit(unsigned char* ws, const float* sub_g, LAS unsigned char* lds, int h, int qb, float negM, float lam) {
;     ...
;         F1 = FLOAD(10); o[0] = __builtin_amdgcn_mfma_f32_32x32x16_bf16(F2, __builtin_bit_cast(bf16x8, pw[0]), o[0], 0, 0, 0); pw[2][0] = cvtpk(pb[0], pb[1]); EXP2(s0, pa, 0); SB();
;         F2 = FLOAD(11); o[1] = __builtin_amdgcn_mfma_f32_32x32x16_bf16(F0, __builtin_bit_cast(bf16x8, pw[0]), o[1], 0, 0, 0); pw[2][1] = cvtpk(pb[2], pb[3]); EXP2(s0, pa, 2); SB();
;         F0 = FLOAD(12); o[2] = __builtin_amdgcn_mfma_f32_32x32x16_bf16(F1, __builtin_bit_cast(bf16x8, pw[0]), o[2], 0, 0, 0); pw[2][2] = cvtpk(pb[4], pb[5]); EXP2(s0, pa, 4); SB();
;         F1 = FLOAD(13); o[3] = __builtin_amdgcn_mfma_f32_32x32x16_bf16(F2, __builtin_bit_cast(bf16x8, pw[0]), o[3], 0, 0, 0); pw[2][3] = cvtpk(pb[6], pb[7]); EXP2(s0, pa, 6); SB();
;         F2 = FLOAD(14); o[0] = __builtin_amdgcn_mfma_f32_32x32x16_bf16(F0, __builtin_bit_cast(bf16x8, pw[1]), o[0], 0, 0, 0); pw[3][0] = cvtpk(pb[8], pb[9]); EXP2(s0, pa, 8); SB();
;         F0 = FLOAD(15); o[1] = __builtin_amdgcn_mfma_f32_32x32x16_bf16(F1, __builtin_bit_cast(bf16x8, pw[1]), o[1], 0, 0, 0); pw[3][1] = cvtpk(pb[10], pb[11]); EXP2(s0, pa, 10); SB();
;         F1 = FLOAD(16); o[2] = __builtin_amdgcn_mfma_f32_32x32x16_bf16(F2, __builtin_bit_cast(bf16x8, pw[1]), o[2], 0, 0, 0); pw[3][2] = cvtpk(pb[12], pb[13]); EXP2(s0, pa, 12); SB();
;         F2 = FLOAD(17); o[3] = __builtin_amdgcn_mfma_f32_32x32x16_bf16(F0, __builtin_bit_cast(bf16x8, pw[1]), o[3], 0, 0, 0); pw[3][3] = cvtpk(pb[14], pb[15]); EXP2(s0, pa, 14); SB();
;         F0 = FLOAD(18); o[0] = __builtin_amdgcn_mfma_f32_32x32x16_bf16(F1, __builtin_bit_cast(bf16x8, pw[2]), o[0], 0, 0, 0); EXP2(s1, pb, 0); SB();
;         F1 = FLOAD(19); o[1] = __builtin_amdgcn_mfma_f32_32x32x16_bf16(F2, __builtin_bit_cast(bf16x8, pw[2]), o[1], 0, 0, 0); EXP2(s1, pb, 2); SB();
;         F2 = FLOAD(20); o[2] = __builtin_amdgcn_mfma_f32_32x32x16_bf16(F0, __builtin_bit_cast(bf16x8, pw[2]), o[2], 0, 0, 0); EXP2(s1, pb, 4); SB();
;         F0 = FLOAD(21); o[3] = __builtin_amdgcn_mfma_f32_32x32x16_bf16(F1, __builtin_bit_cast(bf16x8, pw[2]), o[3], 0, 0, 0); EXP2(s1, pb, 6); SB();
;         F1 = FLOAD(22); o[0] = __builtin_amdgcn_mfma_f32_32x32x16_bf16(F2, __builtin_bit_cast(bf16x8, pw[3]), o[0], 0, 0, 0); EXP2(s1, pb, 8); SB();
	s_waitcnt lgkmcnt(1)
	v_mfma_f32_16x16x32_bf16 v[64:67], v[4:7], v[232:235], v[64:67]
	s_add_i32 m0, s8, 0x10000
	ds_read_b128 v[224:227], v249 offset:55296
	global_load_lds_dwordx4 v140, s[98:99]
	v_exp_f32_e32 v183, v80
	v_cvt_pk_bf16_f32 v228, v203, v204
	v_mfma_f32_16x16x32_bf16 v[68:71], v[4:7], v[236:239], v[68:71]
	v_exp_f32_e32 v184, v81
	v_mfma_f32_16x16x32_bf16 v[72:75], v[8:11], v[232:235], v[72:75]
	s_add_i32 m0, m0, 0x4000
	ds_read_b128 v[4:7], v249 offset:57344
	global_load_lds_dwordx4 v144, s[100:101]
	v_exp_f32_e32 v185, v82
	v_cvt_pk_bf16_f32 v229, v205, v206
	v_mfma_f32_16x16x32_bf16 v[76:79], v[8:11], v[236:239], v[76:79]
	v_exp_f32_e32 v186, v83
	s_waitcnt lgkmcnt(1)
	v_mfma_f32_16x16x32_bf16 v[48:51], v[12:15], v[232:235], v[48:51]
	s_add_i32 m0, m0, 0xffffc400
	ds_read_b128 v[8:11], v249 offset:59392
	global_load_lds_dwordx4 v142, s[98:99]
	v_exp_f32_e32 v187, v84
	v_cvt_pk_bf16_f32 v230, v211, v213
	v_mfma_f32_16x16x32_bf16 v[52:55], v[12:15], v[236:239], v[52:55]
	v_exp_f32_e32 v188, v85
	v_mfma_f32_16x16x32_bf16 v[56:59], v[224:227], v[232:235], v[56:59]
	s_add_i32 m0, m0, 0x4000
	ds_read_b128 v[12:15], v249 offset:61440
	global_load_lds_dwordx4 v146, s[100:101]
	s_add_u32 s98, s98, 0x20000
	s_addc_u32 s99, s99, 0
	s_add_u32 s100, s100, 0x80
	s_addc_u32 s101, s101, 0
	v_exp_f32_e32 v189, v86
	v_cvt_pk_bf16_f32 v231, v214, v215
	v_mfma_f32_16x16x32_bf16 v[60:63], v[224:227], v[236:239], v[60:63]
	v_exp_f32_e32 v190, v87
	s_waitcnt lgkmcnt(1)
	v_mfma_f32_16x16x32_bf16 v[32:35], v[4:7], v[232:235], v[32:35]
	ds_read_b128 v[224:227], v249 offset:63488
	v_exp_f32_e32 v191, v88
	v_cvt_pk_bf16_f32 v240, v207, v208
	v_mfma_f32_16x16x32_bf16 v[36:39], v[4:7], v[236:239], v[36:39]
	v_exp_f32_e32 v192, v89
	v_mfma_f32_16x16x32_bf16 v[40:43], v[8:11], v[232:235], v[40:43]
	ds_read_b128 v[4:7], v250 offset:49152
	v_exp_f32_e32 v193, v90
	v_cvt_pk_bf16_f32 v241, v209, v210
	v_mfma_f32_16x16x32_bf16 v[44:47], v[8:11], v[236:239], v[44:47]
	v_exp_f32_e32 v194, v91
	s_waitcnt lgkmcnt(1)
	v_mfma_f32_16x16x32_bf16 v[16:19], v[12:15], v[232:235], v[16:19]
	ds_read_b128 v[8:11], v250 offset:51200
	v_exp_f32_e32 v195, v92
	v_cvt_pk_bf16_f32 v242, v216, v217
	v_mfma_f32_16x16x32_bf16 v[20:23], v[12:15], v[236:239], v[20:23]
	v_exp_f32_e32 v196, v93
	v_mfma_f32_16x16x32_bf16 v[24:27], v[224:227], v[232:235], v[24:27]
	ds_read_b128 v[12:15], v250 offset:53248
	v_exp_f32_e32 v197, v94
	v_cvt_pk_bf16_f32 v243, v218, v219
	v_mfma_f32_16x16x32_bf16 v[28:31], v[224:227], v[236:239], v[28:31]
	v_exp_f32_e32 v199, v95
	s_waitcnt lgkmcnt(1)
	v_mfma_f32_16x16x32_bf16 v[64:67], v[4:7], v[228:231], v[64:67]
	ds_read_b128 v[224:227], v250 offset:55296
	v_exp_f32_e32 v203, v96
	v_mfma_f32_16x16x32_bf16 v[68:71], v[4:7], v[240:243], v[68:71]
	v_exp_f32_e32 v204, v97
	v_mfma_f32_16x16x32_bf16 v[72:75], v[8:11], v[228:231], v[72:75]
	ds_read_b128 v[4:7], v250 offset:57344
	v_exp_f32_e32 v205, v98
	v_mfma_f32_16x16x32_bf16 v[76:79], v[8:11], v[240:243], v[76:79]
	v_exp_f32_e32 v206, v99
	s_waitcnt lgkmcnt(1)
	v_mfma_f32_16x16x32_bf16 v[48:51], v[12:15], v[228:231], v[48:51]
	ds_read_b128 v[8:11], v250 offset:59392
	v_exp_f32_e32 v207, v100
	v_mfma_f32_16x16x32_bf16 v[52:55], v[12:15], v[240:243], v[52:55]
	v_exp_f32_e32 v208, v101
	v_mfma_f32_16x16x32_bf16 v[56:59], v[224:227], v[228:231], v[56:59]
	ds_read_b128 v[12:15], v250 offset:61440
	v_exp_f32_e32 v209, v102
	v_mfma_f32_16x16x32_bf16 v[60:63], v[224:227], v[240:243], v[60:63]
	v_exp_f32_e32 v210, v103
	s_waitcnt lgkmcnt(1)
	v_mfma_f32_16x16x32_bf16 v[32:35], v[4:7], v[228:231], v[32:35]
	ds_read_b128 v[224:227], v250 offset:63488
	v_exp_f32_e32 v211, v104
	v_mfma_f32_16x16x32_bf16 v[36:39], v[4:7], v[240:243], v[36:39]
	v_exp_f32_e32 v213, v105
	v_mfma_f32_16x16x32_bf16 v[40:43], v[8:11], v[228:231], v[40:43]
	ds_read_b128 v[4:7], v198 offset:32768
	v_exp_f32_e32 v214, v106
	v_mfma_f32_16x16x32_bf16 v[44:47], v[8:11], v[240:243], v[44:47]
	v_exp_f32_e32 v215, v107
	s_waitcnt lgkmcnt(1)
	v_mfma_f32_16x16x32_bf16 v[16:19], v[12:15], v[228:231], v[16:19]
	ds_read_b128 v[8:11], v200 offset:32768
	v_exp_f32_e32 v216, v108
	v_mfma_f32_16x16x32_bf16 v[20:23], v[12:15], v[240:243], v[20:23]
	v_exp_f32_e32 v217, v109
	v_mfma_f32_16x16x32_bf16 v[24:27], v[224:227], v[228:231], v[24:27]
	ds_read_b128 v[12:15], v198 offset:34816
	v_exp_f32_e32 v218, v110
	v_mfma_f32_16x16x32_bf16 v[28:31], v[224:227], v[240:243], v[28:31]
	v_exp_f32_e32 v219, v111
	s_add_i32 s33, s33, 1
	s_branch .Lattn_c1
